# weight-conversion tiles: three extra cache-warming loads (+16/+32/+48 rows) issued with the first row-group load so the later serialized loads hit in cache
# speedup vs baseline: 1.0325x; 1.0116x over previous
; DI int otid() { int z; asm volatile("s_mov_b32 %0, 0" : "=s"(z)); return (int)threadIdx.x + z; }
; DI void cvt_tile(const CvtSeg& s, int tile, char* smem) {
;   float* T = (float*)smem;
;   const int tid = otid();
;   const int nkt = s.K >> 6;
;   const int kt = tile % nkt, nt = tile / nkt;
;   const int k0 = kt * 64, n0 = nt * 64;
;   __syncthreads();
; #pragma unroll
;   for (int i = 0; i < 4; ++i) {
;     const int k = i * 16 + (tid >> 4), n4 = (tid & 15) * 4;
;     float4 v = make_float4(0.f, 0.f, 0.f, 0.f);
;     if (n0 + n4 < s.ncols) {
;       v = *(const float4*)(s.src + (size_t)(k0 + k) * s.lds + s.sc0 + n0 + n4);
; __global__ void __launch_bounds__(256, LB2) mega(Params p, int ph_lo, int ph_hi) {
;     ...
;       for (;;) {
;         const int t = fetch_task(CTR + 32 + ph);
;         if (t >= cw4) break;
;         for (int q = 0; q < 4; ++q) {
;           const int ci = t * 4 + q;
;           if (ci < cw) cvt_set_task(p, SET_OUT, layer, ci, smem);
;         }
.LBB0_221:
	s_or_b64 exec, exec, s[8:9]
	s_waitcnt lgkmcnt(0)
	s_barrier
	ds_read_b32 v0, v219
	s_movk_i32 s8, 0x13f
	s_waitcnt lgkmcnt(0)
	v_cmp_lt_i32_e32 vcc, s8, v0
	v_readfirstlane_b32 s10, v0
	s_mov_b64 s[8:9], -1
	s_cbranch_vccnz .LBB0_216
	v_readlane_b32 s8, v255, 4
	v_readlane_b32 s9, v255, 5
	s_load_dwordx2 s[8:9], s[8:9], 0x38
	s_lshl_b32 s16, s10, 2
	s_mov_b32 s11, 0
	v_mov_b32_e32 v4, 0
	v_add_u32_e32 v10, s11, v189
	s_mul_hi_i32 s11, s16, 0x66666667
	s_waitcnt lgkmcnt(0)
	s_add_u32 s17, s8, s15
	s_addc_u32 s18, s9, s14
	s_lshr_b32 s8, s11, 31
	s_lshr_b32 s9, s11, 4
	s_add_i32 s8, s9, s8
	s_mul_hi_i32 s9, s10, 0x66666667
	s_mul_i32 s8, s8, 40
	s_lshr_b32 s10, s9, 31
	s_lshr_b32 s9, s9, 2
	s_sub_i32 s8, s16, s8
	s_add_i32 s9, s9, s10
	s_lshl_b32 s10, s8, 6
	s_lshl_b32 s8, s9, 6
	s_ashr_i32 s9, s8, 31
	v_lshlrev_b32_e32 v0, 2, v10
	s_lshl_b64 s[12:13], s[8:9], 2
	v_and_b32_e32 v0, 60, v0
	s_add_u32 s12, s17, s12
	v_or_b32_e32 v2, s8, v0
	s_addc_u32 s13, s18, s13
	v_lshlrev_b32_e32 v0, 2, v0
	v_ashrrev_i32_e32 v11, 4, v10
	v_cmp_gt_i32_e32 vcc, s43, v2
	v_lshl_add_u64 v[8:9], s[12:13], 0, v[0:1]
	v_mov_b32_e32 v2, 0
	v_mov_b32_e32 v5, 0
	v_mov_b32_e32 v6, 0
	v_mov_b32_e32 v7, 0
	s_barrier
	s_and_saveexec_b64 s[12:13], vcc
	s_cbranch_execz .LBB0_224
	v_add_u32_e32 v4, s10, v11
	v_ashrrev_i32_e32 v5, 31, v4
	v_lshlrev_b64 v[4:5], 13, v[4:5]
	v_lshl_add_u64 v[4:5], v[8:9], 0, v[4:5]
	v_mov_b32_e32 v44, 0x20000
	v_mov_b32_e32 v45, 0
	v_lshl_add_u64 v[46:47], v[4:5], 0, v[44:45]
	global_load_dwordx4 v[32:35], v[46:47], off
	v_lshl_add_u64 v[46:47], v[46:47], 0, v[44:45]
	global_load_dwordx4 v[36:39], v[46:47], off
	v_lshl_add_u64 v[46:47], v[46:47], 0, v[44:45]
	global_load_dwordx4 v[40:43], v[46:47], off
	global_load_dwordx4 v[4:7], v[4:5], off

; DI int otid() { int z; asm volatile("s_mov_b32 %0, 0" : "=s"(z)); return (int)threadIdx.x + z; }
; DI void cvt_tile(const CvtSeg& s, int tile, char* smem) {
;   float* T = (float*)smem;
;   const int tid = otid();
;   const int nkt = s.K >> 6;
;   const int kt = tile % nkt, nt = tile / nkt;
;   const int k0 = kt * 64, n0 = nt * 64;
;   __syncthreads();
; #pragma unroll
;   for (int i = 0; i < 4; ++i) {
;     const int k = i * 16 + (tid >> 4), n4 = (tid & 15) * 4;
;     float4 v = make_float4(0.f, 0.f, 0.f, 0.f);
;     if (n0 + n4 < s.ncols) {
;       v = *(const float4*)(s.src + (size_t)(k0 + k) * s.lds + s.sc0 + n0 + n4);
;     ...
;   __syncthreads();
; #pragma unroll
;   for (int j = 0; j < 2; ++j) {
;     int c = tid + 256 * j;
;     int n = c >> 3, kc = (c & 7) * 8;
;     float v[8];
; #pragma unroll
;     for (int e = 0; e < 8; ++e) v[e] = T[(kc + e) * 65 + n];
;     *(uint4*)(s.dst + (size_t)(s.dr0 + n0 + n) * s.ldd + k0 + kc) = pack8(v);
;   }
.LBB0_230:
	s_or_b64 exec, exec, s[12:13]
	v_add_u32_e32 v6, 0x30c0, v0
	v_add_u32_e32 v0, 0x30c8, v0
	s_waitcnt vmcnt(0)
	ds_write2_b32 v0, v4, v5 offset1:1
	v_lshlrev_b32_e32 v0, 3, v10
	v_and_b32_e32 v0, 56, v0
	v_mul_u32_u24_e32 v11, 0x104, v0
	v_ashrrev_i32_e32 v12, 3, v10
	ds_write2_b32 v6, v2, v3 offset1:1
	v_lshl_add_u32 v6, v12, 2, v11
	v_add_u32_e32 v8, 0x400, v6
	s_waitcnt lgkmcnt(0)
	s_barrier
	ds_read2_b32 v[2:3], v6 offset1:65
	ds_read2_b32 v[4:5], v6 offset0:130 offset1:195
	ds_read2_b32 v[6:7], v8 offset0:4 offset1:69
	ds_read2_b32 v[8:9], v8 offset0:134 offset1:199
	s_ashr_i32 s11, s10, 31
	s_lshl_b64 s[10:11], s[10:11], 1
	s_waitcnt lgkmcnt(3)
	v_cvt_pk_bf16_f32 v2, v2, v3
	s_waitcnt lgkmcnt(2)
	v_cvt_pk_bf16_f32 v3, v4, v5
	s_waitcnt lgkmcnt(1)
	v_cvt_pk_bf16_f32 v4, v6, v7
	s_waitcnt lgkmcnt(0)
	v_cvt_pk_bf16_f32 v5, v8, v9
	v_add_u32_e32 v8, s8, v12
	v_mov_b64_e32 v[6:7], s[4:5]
	v_mad_i64_i32 v[8:9], s[12:13], v8, s74, v[6:7]
	v_lshl_add_u64 v[8:9], v[8:9], 0, s[10:11]
	v_lshlrev_b32_e32 v0, 1, v0
	v_lshl_add_u64 v[8:9], v[8:9], 0, v[0:1]
	global_store_dwordx4 v[8:9], v[2:5], off
	s_nop 1
	v_add_u32_e32 v2, 0x100, v10
	v_ashrrev_i32_e32 v12, 3, v2
	v_lshl_add_u32 v8, v12, 2, v11
	ds_read2_b32 v[2:3], v8 offset1:65
	ds_read2_b32 v[4:5], v8 offset0:130 offset1:195
	v_add_u32_e32 v10, 0x400, v8
	ds_read2_b32 v[8:9], v10 offset0:4 offset1:69
	ds_read2_b32 v[10:11], v10 offset0:134 offset1:199
	s_waitcnt lgkmcnt(3)
	v_cvt_pk_bf16_f32 v2, v2, v3
	s_waitcnt lgkmcnt(2)
	v_cvt_pk_bf16_f32 v3, v4, v5
	s_waitcnt lgkmcnt(1)
	v_cvt_pk_bf16_f32 v4, v8, v9
	v_add_u32_e32 v8, s8, v12
	v_mad_i64_i32 v[6:7], s[8:9], v8, s74, v[6:7]
	v_lshl_add_u64 v[6:7], v[6:7], 0, s[10:11]
	s_waitcnt lgkmcnt(0)
	v_cvt_pk_bf16_f32 v5, v10, v11
	v_lshl_add_u64 v[6:7], v[6:7], 0, v[0:1]
	v_readlane_b32 s8, v255, 4
	global_store_dwordx4 v[6:7], v[2:5], off
	v_readlane_b32 s9, v255, 5
	s_load_dwordx2 s[8:9], s[8:9], 0x38
	s_or_b32 s10, s16, 1
	v_mov_b32_e32 v4, 0
	v_mov_b32_e32 v5, 0
	v_mov_b32_e32 v6, 0
	s_waitcnt lgkmcnt(0)
	s_add_u32 s11, s8, s15
	s_mov_b32 s8, 0
	s_addc_u32 s17, s9, s14
	v_add_u32_e32 v10, s8, v189
	s_mul_hi_i32 s8, s10, 0x66666667
	s_lshr_b32 s9, s8, 31
	s_ashr_i32 s8, s8, 4
	s_add_i32 s8, s8, s9
	s_mul_i32 s9, s8, 40
	s_sub_i32 s9, s10, s9
	s_lshl_b32 s8, s8, 6
	s_lshl_b32 s10, s9, 6
	s_ashr_i32 s9, s8, 31
	v_lshlrev_b32_e32 v0, 2, v10
	s_lshl_b64 s[12:13], s[8:9], 2
	v_and_b32_e32 v0, 60, v0
	s_add_u32 s12, s11, s12
	v_or_b32_e32 v2, s8, v0
	s_addc_u32 s13, s17, s13
	v_lshlrev_b32_e32 v0, 2, v0
	v_ashrrev_i32_e32 v11, 4, v10
	v_cmp_gt_i32_e32 vcc, s43, v2
	v_lshl_add_u64 v[8:9], s[12:13], 0, v[0:1]
	v_mov_b32_e32 v2, 0
	v_mov_b32_e32 v7, 0
	s_barrier
	s_and_saveexec_b64 s[12:13], vcc
	s_cbranch_execz .LBB0_232
	v_add_u32_e32 v4, s10, v11
	v_ashrrev_i32_e32 v5, 31, v4
	v_lshlrev_b64 v[4:5], 13, v[4:5]
	v_lshl_add_u64 v[4:5], v[8:9], 0, v[4:5]
	v_mov_b32_e32 v44, 0x20000
	v_mov_b32_e32 v45, 0
	v_lshl_add_u64 v[46:47], v[4:5], 0, v[44:45]
	global_load_dwordx4 v[32:35], v[46:47], off
	v_lshl_add_u64 v[46:47], v[46:47], 0, v[44:45]
	global_load_dwordx4 v[36:39], v[46:47], off
	v_lshl_add_u64 v[46:47], v[46:47], 0, v[44:45]
	global_load_dwordx4 v[40:43], v[46:47], off
	global_load_dwordx4 v[4:7], v[4:5], off

; DI int otid() { int z; asm volatile("s_mov_b32 %0, 0" : "=s"(z)); return (int)threadIdx.x + z; }
; DI void cvt_tile(const CvtSeg& s, int tile, char* smem) {
;   float* T = (float*)smem;
;   const int tid = otid();
;   const int nkt = s.K >> 6;
;   const int kt = tile % nkt, nt = tile / nkt;
;   const int k0 = kt * 64, n0 = nt * 64;
;   __syncthreads();
; #pragma unroll
;   for (int i = 0; i < 4; ++i) {
;     const int k = i * 16 + (tid >> 4), n4 = (tid & 15) * 4;
;     float4 v = make_float4(0.f, 0.f, 0.f, 0.f);
;     if (n0 + n4 < s.ncols) {
;       v = *(const float4*)(s.src + (size_t)(k0 + k) * s.lds + s.sc0 + n0 + n4);
;     ...
;   __syncthreads();
; #pragma unroll
;   for (int j = 0; j < 2; ++j) {
;     int c = tid + 256 * j;
;     int n = c >> 3, kc = (c & 7) * 8;
;     float v[8];
; #pragma unroll
;     for (int e = 0; e < 8; ++e) v[e] = T[(kc + e) * 65 + n];
;     *(uint4*)(s.dst + (size_t)(s.dr0 + n0 + n) * s.ldd + k0 + kc) = pack8(v);
;   }
.LBB0_238:
	s_or_b64 exec, exec, s[12:13]
	v_add_u32_e32 v6, 0x30c0, v0
	v_add_u32_e32 v0, 0x30c8, v0
	s_waitcnt vmcnt(0)
	ds_write2_b32 v0, v4, v5 offset1:1
	v_lshlrev_b32_e32 v0, 3, v10
	v_and_b32_e32 v0, 56, v0
	v_mul_u32_u24_e32 v11, 0x104, v0
	v_ashrrev_i32_e32 v12, 3, v10
	ds_write2_b32 v6, v2, v3 offset1:1
	v_lshl_add_u32 v6, v12, 2, v11
	v_add_u32_e32 v8, 0x400, v6
	s_waitcnt lgkmcnt(0)
	s_barrier
	ds_read2_b32 v[2:3], v6 offset1:65
	ds_read2_b32 v[4:5], v6 offset0:130 offset1:195
	ds_read2_b32 v[6:7], v8 offset0:4 offset1:69
	ds_read2_b32 v[8:9], v8 offset0:134 offset1:199
	s_ashr_i32 s11, s10, 31
	s_lshl_b64 s[10:11], s[10:11], 1
	s_waitcnt lgkmcnt(3)
	v_cvt_pk_bf16_f32 v2, v2, v3
	s_waitcnt lgkmcnt(2)
	v_cvt_pk_bf16_f32 v3, v4, v5
	s_waitcnt lgkmcnt(1)
	v_cvt_pk_bf16_f32 v4, v6, v7
	s_waitcnt lgkmcnt(0)
	v_cvt_pk_bf16_f32 v5, v8, v9
	v_add_u32_e32 v8, s8, v12
	v_mov_b64_e32 v[6:7], s[4:5]
	v_mad_i64_i32 v[8:9], s[12:13], v8, s74, v[6:7]
	v_lshl_add_u64 v[8:9], v[8:9], 0, s[10:11]
	v_lshlrev_b32_e32 v0, 1, v0
	v_lshl_add_u64 v[8:9], v[8:9], 0, v[0:1]
	global_store_dwordx4 v[8:9], v[2:5], off
	s_nop 1
	v_add_u32_e32 v2, 0x100, v10
	v_ashrrev_i32_e32 v12, 3, v2
	v_lshl_add_u32 v8, v12, 2, v11
	ds_read2_b32 v[2:3], v8 offset1:65
	ds_read2_b32 v[4:5], v8 offset0:130 offset1:195
	v_add_u32_e32 v10, 0x400, v8
	ds_read2_b32 v[8:9], v10 offset0:4 offset1:69
	ds_read2_b32 v[10:11], v10 offset0:134 offset1:199
	s_waitcnt lgkmcnt(3)
	v_cvt_pk_bf16_f32 v2, v2, v3
	s_waitcnt lgkmcnt(2)
	v_cvt_pk_bf16_f32 v3, v4, v5
	s_waitcnt lgkmcnt(1)
	v_cvt_pk_bf16_f32 v4, v8, v9
	v_add_u32_e32 v8, s8, v12
	v_mad_i64_i32 v[6:7], s[8:9], v8, s74, v[6:7]
	v_lshl_add_u64 v[6:7], v[6:7], 0, s[10:11]
	s_waitcnt lgkmcnt(0)
	v_cvt_pk_bf16_f32 v5, v10, v11
	v_lshl_add_u64 v[6:7], v[6:7], 0, v[0:1]
	v_readlane_b32 s8, v255, 4
	global_store_dwordx4 v[6:7], v[2:5], off
	v_readlane_b32 s9, v255, 5
	s_load_dwordx2 s[8:9], s[8:9], 0x38
	s_or_b32 s10, s16, 2
	v_mov_b32_e32 v4, 0
	v_mov_b32_e32 v5, 0
	v_mov_b32_e32 v6, 0
	s_waitcnt lgkmcnt(0)
	s_add_u32 s11, s8, s15
	s_mov_b32 s8, 0
	s_addc_u32 s17, s9, s14
	v_add_u32_e32 v10, s8, v189
	s_mul_hi_i32 s8, s10, 0x66666667
	s_lshr_b32 s9, s8, 31
	s_ashr_i32 s8, s8, 4
	s_add_i32 s8, s8, s9
	s_mul_i32 s9, s8, 40
	s_sub_i32 s9, s10, s9
	s_lshl_b32 s8, s8, 6
	s_lshl_b32 s10, s9, 6
	s_ashr_i32 s9, s8, 31
	v_lshlrev_b32_e32 v0, 2, v10
	s_lshl_b64 s[12:13], s[8:9], 2
	v_and_b32_e32 v0, 60, v0
	s_add_u32 s12, s11, s12
	v_or_b32_e32 v2, s8, v0
	s_addc_u32 s13, s17, s13
	v_lshlrev_b32_e32 v0, 2, v0
	v_ashrrev_i32_e32 v11, 4, v10
	v_cmp_gt_i32_e32 vcc, s43, v2
	v_lshl_add_u64 v[8:9], s[12:13], 0, v[0:1]
	v_mov_b32_e32 v2, 0
	v_mov_b32_e32 v7, 0
	s_barrier
	s_and_saveexec_b64 s[12:13], vcc
	s_cbranch_execz .LBB0_240
	v_add_u32_e32 v4, s10, v11
	v_ashrrev_i32_e32 v5, 31, v4
	v_lshlrev_b64 v[4:5], 13, v[4:5]
	v_lshl_add_u64 v[4:5], v[8:9], 0, v[4:5]
	v_mov_b32_e32 v44, 0x20000
	v_mov_b32_e32 v45, 0
	v_lshl_add_u64 v[46:47], v[4:5], 0, v[44:45]
	global_load_dwordx4 v[32:35], v[46:47], off
	v_lshl_add_u64 v[46:47], v[46:47], 0, v[44:45]
	global_load_dwordx4 v[36:39], v[46:47], off
	v_lshl_add_u64 v[46:47], v[46:47], 0, v[44:45]
	global_load_dwordx4 v[40:43], v[46:47], off
	global_load_dwordx4 v[4:7], v[4:5], off

; DI int otid() { int z; asm volatile("s_mov_b32 %0, 0" : "=s"(z)); return (int)threadIdx.x + z; }
; DI void cvt_tile(const CvtSeg& s, int tile, char* smem) {
;   float* T = (float*)smem;
;   const int tid = otid();
;   const int nkt = s.K >> 6;
;   const int kt = tile % nkt, nt = tile / nkt;
;   const int k0 = kt * 64, n0 = nt * 64;
;   __syncthreads();
; #pragma unroll
;   for (int i = 0; i < 4; ++i) {
;     const int k = i * 16 + (tid >> 4), n4 = (tid & 15) * 4;
;     float4 v = make_float4(0.f, 0.f, 0.f, 0.f);
;     if (n0 + n4 < s.ncols) {
;       v = *(const float4*)(s.src + (size_t)(k0 + k) * s.lds + s.sc0 + n0 + n4);
;     ...
;   __syncthreads();
; #pragma unroll
;   for (int j = 0; j < 2; ++j) {
;     int c = tid + 256 * j;
;     int n = c >> 3, kc = (c & 7) * 8;
;     float v[8];
; #pragma unroll
;     for (int e = 0; e < 8; ++e) v[e] = T[(kc + e) * 65 + n];
;     *(uint4*)(s.dst + (size_t)(s.dr0 + n0 + n) * s.ldd + k0 + kc) = pack8(v);
;   }
.LBB0_246:
	s_or_b64 exec, exec, s[12:13]
	v_add_u32_e32 v6, 0x30c0, v0
	v_add_u32_e32 v0, 0x30c8, v0
	s_waitcnt vmcnt(0)
	ds_write2_b32 v0, v4, v5 offset1:1
	v_lshlrev_b32_e32 v0, 3, v10
	v_and_b32_e32 v0, 56, v0
	v_mul_u32_u24_e32 v11, 0x104, v0
	v_ashrrev_i32_e32 v12, 3, v10
	ds_write2_b32 v6, v2, v3 offset1:1
	v_lshl_add_u32 v6, v12, 2, v11
	v_add_u32_e32 v8, 0x400, v6
	s_waitcnt lgkmcnt(0)
	s_barrier
	ds_read2_b32 v[2:3], v6 offset1:65
	ds_read2_b32 v[4:5], v6 offset0:130 offset1:195
	ds_read2_b32 v[6:7], v8 offset0:4 offset1:69
	ds_read2_b32 v[8:9], v8 offset0:134 offset1:199
	s_ashr_i32 s11, s10, 31
	s_lshl_b64 s[10:11], s[10:11], 1
	s_waitcnt lgkmcnt(3)
	v_cvt_pk_bf16_f32 v2, v2, v3
	s_waitcnt lgkmcnt(2)
	v_cvt_pk_bf16_f32 v3, v4, v5
	s_waitcnt lgkmcnt(1)
	v_cvt_pk_bf16_f32 v4, v6, v7
	s_waitcnt lgkmcnt(0)
	v_cvt_pk_bf16_f32 v5, v8, v9
	v_add_u32_e32 v8, s8, v12
	v_mov_b64_e32 v[6:7], s[4:5]
	v_mad_i64_i32 v[8:9], s[12:13], v8, s74, v[6:7]
	v_lshl_add_u64 v[8:9], v[8:9], 0, s[10:11]
	v_lshlrev_b32_e32 v0, 1, v0
	v_lshl_add_u64 v[8:9], v[8:9], 0, v[0:1]
	global_store_dwordx4 v[8:9], v[2:5], off
	s_nop 1
	v_add_u32_e32 v2, 0x100, v10
	v_ashrrev_i32_e32 v12, 3, v2
	v_lshl_add_u32 v8, v12, 2, v11
	ds_read2_b32 v[2:3], v8 offset1:65
	ds_read2_b32 v[4:5], v8 offset0:130 offset1:195
	v_add_u32_e32 v10, 0x400, v8
	ds_read2_b32 v[8:9], v10 offset0:4 offset1:69
	ds_read2_b32 v[10:11], v10 offset0:134 offset1:199
	s_waitcnt lgkmcnt(3)
	v_cvt_pk_bf16_f32 v2, v2, v3
	s_waitcnt lgkmcnt(2)
	v_cvt_pk_bf16_f32 v3, v4, v5
	s_waitcnt lgkmcnt(1)
	v_cvt_pk_bf16_f32 v4, v8, v9
	v_add_u32_e32 v8, s8, v12
	v_mad_i64_i32 v[6:7], s[8:9], v8, s74, v[6:7]
	v_lshl_add_u64 v[6:7], v[6:7], 0, s[10:11]
	s_waitcnt lgkmcnt(0)
	v_cvt_pk_bf16_f32 v5, v10, v11
	v_lshl_add_u64 v[6:7], v[6:7], 0, v[0:1]
	v_readlane_b32 s8, v255, 4
	global_store_dwordx4 v[6:7], v[2:5], off
	v_readlane_b32 s9, v255, 5
	s_load_dwordx2 s[8:9], s[8:9], 0x38
	s_or_b32 s10, s16, 3
	v_mov_b32_e32 v4, 0
	v_mov_b32_e32 v5, 0
	v_mov_b32_e32 v6, 0
	s_waitcnt lgkmcnt(0)
	s_add_u32 s11, s8, s15
	s_mov_b32 s8, 0
	s_addc_u32 s16, s9, s14
	v_add_u32_e32 v10, s8, v189
	s_mul_hi_i32 s8, s10, 0x66666667
	s_lshr_b32 s9, s8, 31
	s_ashr_i32 s8, s8, 4
	s_add_i32 s8, s8, s9
	s_mul_i32 s9, s8, 40
	s_sub_i32 s9, s10, s9
	s_lshl_b32 s8, s8, 6
	s_lshl_b32 s10, s9, 6
	s_ashr_i32 s9, s8, 31
	v_lshlrev_b32_e32 v0, 2, v10
	s_lshl_b64 s[12:13], s[8:9], 2
	v_and_b32_e32 v0, 60, v0
	s_add_u32 s12, s11, s12
	v_or_b32_e32 v2, s8, v0
	s_addc_u32 s13, s16, s13
	v_lshlrev_b32_e32 v0, 2, v0
	v_ashrrev_i32_e32 v11, 4, v10
	v_cmp_gt_i32_e32 vcc, s43, v2
	v_lshl_add_u64 v[8:9], s[12:13], 0, v[0:1]
	v_mov_b32_e32 v2, 0
	v_mov_b32_e32 v7, 0
	s_barrier
	s_and_saveexec_b64 s[12:13], vcc
	s_cbranch_execz .LBB0_248
	v_add_u32_e32 v4, s10, v11
	v_ashrrev_i32_e32 v5, 31, v4
	v_lshlrev_b64 v[4:5], 13, v[4:5]
	v_lshl_add_u64 v[4:5], v[8:9], 0, v[4:5]
	v_mov_b32_e32 v44, 0x20000
	v_mov_b32_e32 v45, 0
	v_lshl_add_u64 v[46:47], v[4:5], 0, v[44:45]
	global_load_dwordx4 v[32:35], v[46:47], off
	v_lshl_add_u64 v[46:47], v[46:47], 0, v[44:45]
	global_load_dwordx4 v[36:39], v[46:47], off
	v_lshl_add_u64 v[46:47], v[46:47], 0, v[44:45]
	global_load_dwordx4 v[40:43], v[46:47], off
	global_load_dwordx4 v[4:7], v[4:5], off

; DI int otid() { int z; asm volatile("s_mov_b32 %0, 0" : "=s"(z)); return (int)threadIdx.x + z; }
; DI void cvt_tile(const CvtSeg& s, int tile, char* smem) {
;   float* T = (float*)smem;
;   const int tid = otid();
;   const int nkt = s.K >> 6;
;   const int kt = tile % nkt, nt = tile / nkt;
;   const int k0 = kt * 64, n0 = nt * 64;
;   __syncthreads();
; #pragma unroll
;   for (int i = 0; i < 4; ++i) {
;     const int k = i * 16 + (tid >> 4), n4 = (tid & 15) * 4;
;     float4 v = make_float4(0.f, 0.f, 0.f, 0.f);
;     if (n0 + n4 < s.ncols) {
;       v = *(const float4*)(s.src + (size_t)(k0 + k) * s.lds + s.sc0 + n0 + n4);
;       if (s.kscale) { float sc = s.kscale[k0 + k]; v.x *= sc; v.y *= sc; v.z *= sc; v.w *= sc; }
.LBB0_993:
	v_cvt_f32_ubyte0_e32 v0, s13
	v_rcp_iflag_f32_e32 v0, v0
	s_mov_b32 s0, 0
	s_sub_i32 s25, 0, s13
	v_add_u32_e32 v14, s0, v189
	v_mul_f32_e32 v0, 0x4f7ffffe, v0
	v_cvt_u32_f32_e32 v0, v0
	s_abs_i32 s24, s17
	s_ashr_i32 s1, s17, 31
	v_ashrrev_i32_e32 v8, 4, v14
	v_readfirstlane_b32 s0, v0
	s_mul_i32 s25, s25, s0
	s_mul_hi_u32 s25, s0, s25
	s_add_i32 s0, s0, s25
	s_mul_hi_u32 s0, s24, s0
	s_mul_i32 s25, s0, s13
	s_sub_i32 s24, s24, s25
	s_add_i32 s26, s0, 1
	s_sub_i32 s25, s24, s13
	s_cmp_ge_u32 s24, s13
	s_cselect_b32 s0, s26, s0
	s_cselect_b32 s24, s25, s24
	s_add_i32 s25, s0, 1
	s_cmp_ge_u32 s24, s13
	s_cselect_b32 s0, s25, s0
	s_xor_b32 s0, s0, s1
	s_sub_i32 s1, s0, s1
	s_mul_i32 s0, s1, s13
	s_lshl_b32 s46, s1, 6
	s_sub_i32 s0, s17, s0
	s_ashr_i32 s47, s46, 31
	s_lshl_b32 s0, s0, 6
	s_lshl_b64 s[24:25], s[46:47], 2
	v_lshlrev_b32_e32 v0, 2, v14
	s_add_u32 s14, s14, s24
	v_and_b32_e32 v0, 60, v0
	s_addc_u32 s15, s15, s25
	v_or_b32_e32 v2, s46, v0
	v_lshlrev_b32_e32 v0, 2, v0
	s_cmp_lg_u64 s[62:63], 0
	v_lshl_add_u64 v[10:11], s[14:15], 0, v[0:1]
	s_cselect_b64 s[14:15], -1, 0
	s_waitcnt lgkmcnt(0)
	v_cndmask_b32_e64 v3, 0, 1, s[14:15]
	v_cmp_gt_i32_e64 s[12:13], s12, v2
	v_mov_b32_e32 v2, 0
	v_cmp_ne_u32_e64 s[14:15], 1, v3
	v_mov_b32_e32 v4, 0
	v_mov_b32_e32 v5, 0
	v_mov_b32_e32 v6, 0
	v_mov_b32_e32 v7, 0
	s_barrier
	s_and_saveexec_b64 s[86:87], s[12:13]
	s_cbranch_execz .LBB0_996
	v_add_u32_e32 v12, s0, v8
	v_mad_i64_i32 v[4:5], s[24:25], s82, v12, 0
	v_lshl_add_u64 v[4:5], v[4:5], 2, v[10:11]
	v_mov_b32_e32 v44, s82
	v_lshlrev_b32_e32 v44, 6, v44
	v_mov_b32_e32 v45, 0
	v_lshl_add_u64 v[46:47], v[4:5], 0, v[44:45]
	global_load_dwordx4 v[32:35], v[46:47], off
	v_lshl_add_u64 v[46:47], v[46:47], 0, v[44:45]
	global_load_dwordx4 v[36:39], v[46:47], off
	v_lshl_add_u64 v[46:47], v[46:47], 0, v[44:45]
	global_load_dwordx4 v[40:43], v[46:47], off
	global_load_dwordx4 v[4:7], v[4:5], off
	s_and_b64 vcc, exec, s[14:15]
	s_cbranch_vccnz .LBB0_996
	v_ashrrev_i32_e32 v13, 31, v12
	v_lshl_add_u64 v[12:13], v[12:13], 2, s[62:63]
	global_load_dword v12, v[12:13], off
	s_waitcnt vmcnt(0)
	v_pk_mul_f32 v[4:5], v[4:5], v[12:13] op_sel_hi:[1,0]
	v_pk_mul_f32 v[6:7], v[6:7], v[12:13] op_sel_hi:[1,0]

; DI int otid() { int z; asm volatile("s_mov_b32 %0, 0" : "=s"(z)); return (int)threadIdx.x + z; }
; DI void cvt_tile(const CvtSeg& s, int tile, char* smem) {
;   float* T = (float*)smem;
;   const int tid = otid();
;   const int nkt = s.K >> 6;
;   const int kt = tile % nkt, nt = tile / nkt;
;   const int k0 = kt * 64, n0 = nt * 64;
;   __syncthreads();
; #pragma unroll
;   for (int i = 0; i < 4; ++i) {
;     const int k = i * 16 + (tid >> 4), n4 = (tid & 15) * 4;
;     float4 v = make_float4(0.f, 0.f, 0.f, 0.f);
;     if (n0 + n4 < s.ncols) {
;       v = *(const float4*)(s.src + (size_t)(k0 + k) * s.lds + s.sc0 + n0 + n4);
;       if (s.kscale) { float sc = s.kscale[k0 + k]; v.x *= sc; v.y *= sc; v.z *= sc; v.w *= sc; }
.LBB0_1010:
	v_readlane_b32 s12, v255, 4
	v_readlane_b32 s13, v255, 5
	s_load_dwordx2 s[14:15], s[12:13], 0xb0
	s_lshl_b64 s[0:1], s[34:35], 2
	s_load_dwordx2 s[12:13], s[12:13], 0xc0
	s_mov_b32 s24, 0
	v_mov_b32_e32 v4, 0
	s_waitcnt lgkmcnt(0)
	s_add_u32 s0, s14, s0
	s_addc_u32 s1, s15, s1
	s_add_u32 s26, s12, s4
	s_addc_u32 s27, s13, s5
	s_ashr_i32 s12, s57, 31
	s_lshr_b32 s12, s12, 29
	s_add_i32 s12, s57, s12
	s_and_b32 s13, s12, 0x3fffff8
	s_lshl_b32 s12, s12, 3
	s_and_b32 s36, s12, 0xffffffc0
	s_sub_i32 s13, s57, s13
	s_ashr_i32 s37, s36, 31
	v_add_u32_e32 v14, s24, v189
	s_lshl_b32 s46, s13, 6
	s_lshl_b64 s[24:25], s[36:37], 2
	s_add_u32 s24, s26, s24
	s_addc_u32 s25, s27, s25
	v_lshlrev_b32_e32 v0, 2, v14
	s_cmp_lg_u64 s[14:15], 0
	v_and_b32_e32 v0, 60, v0
	s_cselect_b64 s[14:15], -1, 0
	v_or_b32_e32 v2, s36, v0
	s_movk_i32 s12, 0x800
	v_lshlrev_b32_e32 v0, 2, v0
	v_cndmask_b32_e64 v3, 0, 1, s[14:15]
	v_ashrrev_i32_e32 v8, 4, v14
	v_cmp_gt_i32_e64 s[12:13], s12, v2
	v_lshl_add_u64 v[10:11], s[24:25], 0, v[0:1]
	v_mov_b32_e32 v2, 0
	v_cmp_ne_u32_e64 s[14:15], 1, v3
	v_mov_b32_e32 v5, 0
	v_mov_b32_e32 v6, 0
	v_mov_b32_e32 v7, 0
	s_barrier
	s_and_saveexec_b64 s[52:53], s[12:13]
	s_cbranch_execz .LBB0_1013
	v_add_u32_e32 v12, s46, v8
	v_ashrrev_i32_e32 v13, 31, v12
	v_lshlrev_b64 v[4:5], 13, v[12:13]
	v_lshl_add_u64 v[4:5], v[10:11], 0, v[4:5]
	v_mov_b32_e32 v44, 0x20000
	v_mov_b32_e32 v45, 0
	v_lshl_add_u64 v[46:47], v[4:5], 0, v[44:45]
	global_load_dwordx4 v[32:35], v[46:47], off
	v_lshl_add_u64 v[46:47], v[46:47], 0, v[44:45]
	global_load_dwordx4 v[36:39], v[46:47], off
	v_lshl_add_u64 v[46:47], v[46:47], 0, v[44:45]
	global_load_dwordx4 v[40:43], v[46:47], off
	global_load_dwordx4 v[4:7], v[4:5], off
	s_and_b64 vcc, exec, s[14:15]
	s_cbranch_vccnz .LBB0_1013
	v_lshl_add_u64 v[12:13], v[12:13], 2, s[0:1]
	global_load_dword v12, v[12:13], off
	s_waitcnt vmcnt(0)
	v_pk_mul_f32 v[4:5], v[4:5], v[12:13] op_sel_hi:[1,0]
	v_pk_mul_f32 v[6:7], v[6:7], v[12:13] op_sel_hi:[1,0]

; DI int otid() { int z; asm volatile("s_mov_b32 %0, 0" : "=s"(z)); return (int)threadIdx.x + z; }
; DI void cvt_tile(const CvtSeg& s, int tile, char* smem) {
;   float* T = (float*)smem;
;   const int tid = otid();
;   const int nkt = s.K >> 6;
;   const int kt = tile % nkt, nt = tile / nkt;
;   const int k0 = kt * 64, n0 = nt * 64;
;   __syncthreads();
; #pragma unroll
;   for (int i = 0; i < 4; ++i) {
;     const int k = i * 16 + (tid >> 4), n4 = (tid & 15) * 4;
;     float4 v = make_float4(0.f, 0.f, 0.f, 0.f);
;     if (n0 + n4 < s.ncols) {
;       v = *(const float4*)(s.src + (size_t)(k0 + k) * s.lds + s.sc0 + n0 + n4);
.LBB0_1027:
	v_readlane_b32 s12, v255, 4
	v_readlane_b32 s13, v255, 5
	s_load_dwordx2 s[12:13], s[12:13], 0xd0
	v_readlane_b32 s16, v255, 38
	v_readlane_b32 s17, v255, 39
	s_mov_b32 s14, 0
	v_mov_b32_e32 v4, 0
	s_waitcnt lgkmcnt(0)
	s_add_u32 s15, s12, s16
	s_addc_u32 s24, s13, s17
	s_ashr_i32 s12, s36, 31
	s_lshr_b32 s12, s12, 26
	v_add_u32_e32 v10, s14, v189
	s_add_i32 s12, s36, s12
	s_andn2_b32 s12, s12, 63
	v_lshlrev_b32_e32 v0, 2, v10
	s_sub_i32 s13, s36, s12
	v_and_b32_e32 v0, 60, v0
	s_lshl_b32 s14, s13, 6
	v_or_b32_e32 v2, s12, v0
	s_movk_i32 s13, 0x100
	v_cmp_gt_i32_e32 vcc, s13, v2
	s_ashr_i32 s13, s12, 31
	s_lshl_b64 s[16:17], s[12:13], 2
	s_add_u32 s16, s15, s16
	s_addc_u32 s17, s24, s17
	v_lshlrev_b32_e32 v0, 2, v0
	v_ashrrev_i32_e32 v11, 4, v10
	v_lshl_add_u64 v[8:9], s[16:17], 0, v[0:1]
	v_mov_b32_e32 v2, 0
	v_mov_b32_e32 v5, 0
	v_mov_b32_e32 v6, 0
	v_mov_b32_e32 v7, 0
	s_barrier
	s_and_saveexec_b64 s[16:17], vcc
	s_cbranch_execz .LBB0_1029
	v_add_u32_e32 v4, s14, v11
	v_ashrrev_i32_e32 v5, 31, v4
	v_lshlrev_b64 v[4:5], 10, v[4:5]
	v_lshl_add_u64 v[4:5], v[8:9], 0, v[4:5]
	v_mov_b32_e32 v44, 0x4000
	v_mov_b32_e32 v45, 0
	v_lshl_add_u64 v[46:47], v[4:5], 0, v[44:45]
	global_load_dwordx4 v[32:35], v[46:47], off
	v_lshl_add_u64 v[46:47], v[46:47], 0, v[44:45]
	global_load_dwordx4 v[36:39], v[46:47], off
	v_lshl_add_u64 v[46:47], v[46:47], 0, v[44:45]
	global_load_dwordx4 v[40:43], v[46:47], off
	global_load_dwordx4 v[4:7], v[4:5], off

; DI int otid() { int z; asm volatile("s_mov_b32 %0, 0" : "=s"(z)); return (int)threadIdx.x + z; }
; DI void cvt_tile(const CvtSeg& s, int tile, char* smem) {
;   float* T = (float*)smem;
;   const int tid = otid();
;   const int nkt = s.K >> 6;
;   const int kt = tile % nkt, nt = tile / nkt;
;   const int k0 = kt * 64, n0 = nt * 64;
;   __syncthreads();
; #pragma unroll
;   for (int i = 0; i < 4; ++i) {
;     const int k = i * 16 + (tid >> 4), n4 = (tid & 15) * 4;
;     float4 v = make_float4(0.f, 0.f, 0.f, 0.f);
;     if (n0 + n4 < s.ncols) {
;       v = *(const float4*)(s.src + (size_t)(k0 + k) * s.lds + s.sc0 + n0 + n4);
.LBB0_1040:
	v_readlane_b32 s12, v255, 4
	v_readlane_b32 s13, v255, 5
	s_load_dwordx2 s[12:13], s[12:13], 0xd0
	v_readlane_b32 s16, v255, 40
	v_readlane_b32 s17, v255, 41
	s_mov_b32 s14, 0
	v_mov_b32_e32 v4, 0
	s_waitcnt lgkmcnt(0)
	s_add_u32 s15, s12, s16
	s_addc_u32 s24, s13, s17
	s_ashr_i32 s12, s37, 31
	s_lshr_b32 s12, s12, 26
	v_add_u32_e32 v10, s14, v189
	s_add_i32 s12, s37, s12
	s_andn2_b32 s12, s12, 63
	v_lshlrev_b32_e32 v0, 2, v10
	s_sub_i32 s13, s37, s12
	v_and_b32_e32 v0, 60, v0
	s_lshl_b32 s14, s13, 6
	v_or_b32_e32 v2, s12, v0
	s_movk_i32 s13, 0x100
	v_cmp_gt_i32_e32 vcc, s13, v2
	s_ashr_i32 s13, s12, 31
	s_lshl_b64 s[16:17], s[12:13], 2
	s_add_u32 s16, s15, s16
	s_addc_u32 s17, s24, s17
	v_lshlrev_b32_e32 v0, 2, v0
	v_ashrrev_i32_e32 v11, 4, v10
	v_lshl_add_u64 v[8:9], s[16:17], 0, v[0:1]
	v_mov_b32_e32 v2, 0
	v_mov_b32_e32 v5, 0
	v_mov_b32_e32 v6, 0
	v_mov_b32_e32 v7, 0
	s_barrier
	s_and_saveexec_b64 s[16:17], vcc
	s_cbranch_execz .LBB0_1042
	v_add_u32_e32 v4, s14, v11
	v_ashrrev_i32_e32 v5, 31, v4
	v_lshlrev_b64 v[4:5], 10, v[4:5]
	v_lshl_add_u64 v[4:5], v[8:9], 0, v[4:5]
	v_mov_b32_e32 v44, 0x4000
	v_mov_b32_e32 v45, 0
	v_lshl_add_u64 v[46:47], v[4:5], 0, v[44:45]
	global_load_dwordx4 v[32:35], v[46:47], off
	v_lshl_add_u64 v[46:47], v[46:47], 0, v[44:45]
	global_load_dwordx4 v[36:39], v[46:47], off
	v_lshl_add_u64 v[46:47], v[46:47], 0, v[44:45]
	global_load_dwordx4 v[40:43], v[46:47], off
	global_load_dwordx4 v[4:7], v[4:5], off

; DI int otid() { int z; asm volatile("s_mov_b32 %0, 0" : "=s"(z)); return (int)threadIdx.x + z; }
; DI void cvt_tile(const CvtSeg& s, int tile, char* smem) {
;   float* T = (float*)smem;
;   const int tid = otid();
;   const int nkt = s.K >> 6;
;   const int kt = tile % nkt, nt = tile / nkt;
;   const int k0 = kt * 64, n0 = nt * 64;
;   __syncthreads();
; #pragma unroll
;   for (int i = 0; i < 4; ++i) {
;     const int k = i * 16 + (tid >> 4), n4 = (tid & 15) * 4;
;     float4 v = make_float4(0.f, 0.f, 0.f, 0.f);
;     if (n0 + n4 < s.ncols) {
;       v = *(const float4*)(s.src + (size_t)(k0 + k) * s.lds + s.sc0 + n0 + n4);
.LBB0_1049:
	s_cmp_gt_i32 s36, 7
	s_cselect_b64 s[0:1], -1, 0
	s_cmp_lt_i32 s36, 8
	s_mov_b64 s[12:13], -1
	s_cbranch_scc0 .LBB0_1059
	v_readlane_b32 s12, v255, 4
	v_readlane_b32 s13, v255, 5
	s_load_dwordx2 s[12:13], s[12:13], 0xd8
	v_readlane_b32 s16, v255, 52
	v_readlane_b32 s17, v255, 53
	s_mov_b32 s14, 0
	v_mov_b32_e32 v4, 0
	s_waitcnt lgkmcnt(0)
	s_add_u32 s15, s12, s16
	s_addc_u32 s24, s13, s17
	s_ashr_i32 s12, s36, 31
	s_lshr_b32 s12, s12, 30
	v_add_u32_e32 v10, s14, v189
	s_add_i32 s12, s36, s12
	s_and_b32 s13, s12, 0x3fffffc
	s_lshl_b32 s12, s12, 4
	v_lshlrev_b32_e32 v0, 2, v10
	s_sub_i32 s13, s36, s13
	s_andn2_b32 s12, s12, 63
	v_and_b32_e32 v0, 60, v0
	s_lshl_b32 s14, s13, 6
	v_or_b32_e32 v2, s12, v0
	s_movk_i32 s13, 0x80
	v_cmp_gt_i32_e32 vcc, s13, v2
	s_ashr_i32 s13, s12, 31
	s_lshl_b64 s[16:17], s[12:13], 2
	s_add_u32 s16, s15, s16
	s_addc_u32 s17, s24, s17
	v_lshlrev_b32_e32 v0, 2, v0
	v_ashrrev_i32_e32 v11, 4, v10
	v_lshl_add_u64 v[8:9], s[16:17], 0, v[0:1]
	v_mov_b32_e32 v2, 0
	v_mov_b32_e32 v5, 0
	v_mov_b32_e32 v6, 0
	v_mov_b32_e32 v7, 0
	s_barrier
	s_and_saveexec_b64 s[16:17], vcc
	s_cbranch_execz .LBB0_1052
	v_add_u32_e32 v4, s14, v11
	v_ashrrev_i32_e32 v5, 31, v4
	v_lshlrev_b64 v[4:5], 9, v[4:5]
	v_lshl_add_u64 v[4:5], v[8:9], 0, v[4:5]
	v_mov_b32_e32 v44, 0x2000
	v_mov_b32_e32 v45, 0
	v_lshl_add_u64 v[46:47], v[4:5], 0, v[44:45]
	global_load_dwordx4 v[32:35], v[46:47], off
	v_lshl_add_u64 v[46:47], v[46:47], 0, v[44:45]
	global_load_dwordx4 v[36:39], v[46:47], off
	v_lshl_add_u64 v[46:47], v[46:47], 0, v[44:45]
	global_load_dwordx4 v[40:43], v[46:47], off
	global_load_dwordx4 v[4:7], v[4:5], off

; DI int otid() { int z; asm volatile("s_mov_b32 %0, 0" : "=s"(z)); return (int)threadIdx.x + z; }
; DI void cvt_tile(const CvtSeg& s, int tile, char* smem) {
;   float* T = (float*)smem;
;   const int tid = otid();
;   const int nkt = s.K >> 6;
;   const int kt = tile % nkt, nt = tile / nkt;
;   const int k0 = kt * 64, n0 = nt * 64;
;   __syncthreads();
; #pragma unroll
;   for (int i = 0; i < 4; ++i) {
;     const int k = i * 16 + (tid >> 4), n4 = (tid & 15) * 4;
;     float4 v = make_float4(0.f, 0.f, 0.f, 0.f);
;     if (n0 + n4 < s.ncols) {
;       v = *(const float4*)(s.src + (size_t)(k0 + k) * s.lds + s.sc0 + n0 + n4);
.LBB0_1061:
	s_cmp_lt_i32 s36, 8
	s_cselect_b64 s[12:13], -1, 0
	s_and_b64 s[0:1], s[0:1], s[12:13]
	s_andn2_b64 vcc, exec, s[0:1]
	s_cbranch_vccnz .LBB0_1071
	v_readlane_b32 s0, v255, 4
	v_readlane_b32 s1, v255, 5
	s_load_dwordx2 s[0:1], s[0:1], 0xd8
	v_readlane_b32 s14, v255, 56
	v_readlane_b32 s15, v255, 57
	s_mov_b32 s12, 0
	v_mov_b32_e32 v4, 0
	s_waitcnt lgkmcnt(0)
	s_add_u32 s13, s0, s14
	s_addc_u32 s16, s1, s15
	s_ashr_i32 s0, s36, 31
	s_lshr_b32 s0, s0, 30
	v_add_u32_e32 v10, s12, v189
	s_add_i32 s0, s36, s0
	s_and_b32 s1, s0, 0x3fffffc
	s_lshl_b32 s0, s0, 4
	v_lshlrev_b32_e32 v0, 2, v10
	s_sub_i32 s1, s36, s1
	s_andn2_b32 s0, s0, 63
	v_and_b32_e32 v0, 60, v0
	s_lshl_b32 s12, s1, 6
	v_or_b32_e32 v2, s0, v0
	s_movk_i32 s1, 0x80
	v_cmp_gt_i32_e32 vcc, s1, v2
	s_ashr_i32 s1, s0, 31
	s_lshl_b64 s[14:15], s[0:1], 2
	s_add_u32 s14, s13, s14
	s_addc_u32 s15, s16, s15
	v_lshlrev_b32_e32 v0, 2, v0
	v_ashrrev_i32_e32 v11, 4, v10
	v_lshl_add_u64 v[8:9], s[14:15], 0, v[0:1]
	v_mov_b32_e32 v2, 0
	v_mov_b32_e32 v5, 0
	v_mov_b32_e32 v6, 0
	v_mov_b32_e32 v7, 0
	s_barrier
	s_and_saveexec_b64 s[14:15], vcc
	s_cbranch_execz .LBB0_1064
	v_add_u32_e32 v4, s12, v11
	v_ashrrev_i32_e32 v5, 31, v4
	v_lshlrev_b64 v[4:5], 9, v[4:5]
	v_lshl_add_u64 v[4:5], v[8:9], 0, v[4:5]
	v_mov_b32_e32 v44, 0x2000
	v_mov_b32_e32 v45, 0
	v_lshl_add_u64 v[46:47], v[4:5], 0, v[44:45]
	global_load_dwordx4 v[32:35], v[46:47], off
	v_lshl_add_u64 v[46:47], v[46:47], 0, v[44:45]
	global_load_dwordx4 v[36:39], v[46:47], off
	v_lshl_add_u64 v[46:47], v[46:47], 0, v[44:45]
	global_load_dwordx4 v[40:43], v[46:47], off
	global_load_dwordx4 v[4:7], v[4:5], off

; DI int otid() { int z; asm volatile("s_mov_b32 %0, 0" : "=s"(z)); return (int)threadIdx.x + z; }
; DI void cvt_tile(const CvtSeg& s, int tile, char* smem) {
;   float* T = (float*)smem;
;   const int tid = otid();
;   const int nkt = s.K >> 6;
;   const int kt = tile % nkt, nt = tile / nkt;
;   const int k0 = kt * 64, n0 = nt * 64;
;   __syncthreads();
; #pragma unroll
;   for (int i = 0; i < 4; ++i) {
;     const int k = i * 16 + (tid >> 4), n4 = (tid & 15) * 4;
;     float4 v = make_float4(0.f, 0.f, 0.f, 0.f);
;     if (n0 + n4 < s.ncols) {
;       v = *(const float4*)(s.src + (size_t)(k0 + k) * s.lds + s.sc0 + n0 + n4);
.LBB0_1072:
	s_andn2_b64 vcc, exec, s[0:1]
	s_cbranch_vccnz .LBB0_1082
	v_readlane_b32 s0, v255, 4
	v_readlane_b32 s1, v255, 5
	s_load_dwordx2 s[0:1], s[0:1], 0x40
	s_sub_i32 s12, s97, s56
	s_mov_b32 s13, 0
	v_mov_b32_e32 v4, 0
	v_add_u32_e32 v10, s13, v189
	s_waitcnt lgkmcnt(0)
	s_add_u32 s13, s0, s42
	s_addc_u32 s16, s1, s43
	s_ashr_i32 s0, s12, 31
	s_lshr_b32 s0, s0, 27
	s_add_i32 s0, s12, s0
	s_and_b32 s1, s0, 0x3ffffe0
	s_lshl_b32 s0, s0, 1
	s_sub_i32 s1, s12, s1
	s_andn2_b32 s0, s0, 63
	s_lshl_b32 s12, s1, 6
	s_ashr_i32 s1, s0, 31
	v_lshlrev_b32_e32 v0, 2, v10
	s_lshl_b64 s[14:15], s[0:1], 2
	v_and_b32_e32 v0, 60, v0
	s_add_u32 s14, s13, s14
	v_or_b32_e32 v2, s0, v0
	s_addc_u32 s15, s16, s15
	v_lshlrev_b32_e32 v0, 2, v0
	v_ashrrev_i32_e32 v11, 4, v10
	v_cmp_gt_i32_e32 vcc, s63, v2
	v_lshl_add_u64 v[8:9], s[14:15], 0, v[0:1]
	v_mov_b32_e32 v2, 0
	v_mov_b32_e32 v5, 0
	v_mov_b32_e32 v6, 0
	v_mov_b32_e32 v7, 0
	s_barrier
	s_and_saveexec_b64 s[14:15], vcc
	s_cbranch_execz .LBB0_1075
	v_add_u32_e32 v4, s12, v11
	v_ashrrev_i32_e32 v5, 31, v4
	v_lshlrev_b64 v[4:5], 12, v[4:5]
	v_lshl_add_u64 v[4:5], v[8:9], 0, v[4:5]
	v_mov_b32_e32 v44, 0x10000
	v_mov_b32_e32 v45, 0
	v_lshl_add_u64 v[46:47], v[4:5], 0, v[44:45]
	global_load_dwordx4 v[32:35], v[46:47], off
	v_lshl_add_u64 v[46:47], v[46:47], 0, v[44:45]
	global_load_dwordx4 v[36:39], v[46:47], off
	v_lshl_add_u64 v[46:47], v[46:47], 0, v[44:45]
	global_load_dwordx4 v[40:43], v[46:47], off
	global_load_dwordx4 v[4:7], v[4:5], off

; DI int otid() { int z; asm volatile("s_mov_b32 %0, 0" : "=s"(z)); return (int)threadIdx.x + z; }
; DI void cvt_tile(const CvtSeg& s, int tile, char* smem) {
;   float* T = (float*)smem;
;   const int tid = otid();
;   const int nkt = s.K >> 6;
;   const int kt = tile % nkt, nt = tile / nkt;
;   const int k0 = kt * 64, n0 = nt * 64;
;   __syncthreads();
; #pragma unroll
;   for (int i = 0; i < 4; ++i) {
;     const int k = i * 16 + (tid >> 4), n4 = (tid & 15) * 4;
;     float4 v = make_float4(0.f, 0.f, 0.f, 0.f);
;     if (n0 + n4 < s.ncols) {
;       v = *(const float4*)(s.src + (size_t)(k0 + k) * s.lds + s.sc0 + n0 + n4);
.LBB0_1088:
	s_load_dwordx2 s[12:13], s[60:61], 0x0
	s_mov_b32 s14, 0
	v_mov_b32_e32 v4, 0
	v_add_u32_e32 v10, s14, v189
	v_lshlrev_b32_e32 v0, 2, v10
	s_waitcnt lgkmcnt(0)
	s_add_u32 s15, s12, s90
	s_addc_u32 s24, s13, s11
	s_ashr_i32 s12, s97, 31
	s_lshr_b32 s12, s12, 27
	s_add_i32 s12, s97, s12
	s_and_b32 s13, s12, 0x3ffffe0
	s_lshl_b32 s12, s12, 1
	s_sub_i32 s13, s97, s13
	s_andn2_b32 s12, s12, 63
	s_lshl_b32 s14, s13, 6
	s_ashr_i32 s13, s12, 31
	s_lshl_b64 s[16:17], s[12:13], 2
	v_and_b32_e32 v0, 60, v0
	s_add_u32 s16, s15, s16
	v_or_b32_e32 v2, s12, v0
	s_addc_u32 s17, s24, s17
	v_lshlrev_b32_e32 v0, 2, v0
	v_ashrrev_i32_e32 v11, 4, v10
	v_cmp_gt_i32_e32 vcc, s10, v2
	v_lshl_add_u64 v[8:9], s[16:17], 0, v[0:1]
	v_mov_b32_e32 v2, 0
	v_mov_b32_e32 v5, 0
	v_mov_b32_e32 v6, 0
	v_mov_b32_e32 v7, 0
	s_barrier
	s_and_saveexec_b64 s[16:17], vcc
	s_cbranch_execz .LBB0_1090
	v_add_u32_e32 v3, s14, v11
	v_mad_i64_i32 v[4:5], s[24:25], s38, v3, 0
	v_lshl_add_u64 v[4:5], v[4:5], 2, v[8:9]
	v_mov_b32_e32 v44, s38
	v_lshlrev_b32_e32 v44, 6, v44
	v_mov_b32_e32 v45, 0
	v_lshl_add_u64 v[46:47], v[4:5], 0, v[44:45]
	global_load_dwordx4 v[32:35], v[46:47], off
	v_lshl_add_u64 v[46:47], v[46:47], 0, v[44:45]
	global_load_dwordx4 v[36:39], v[46:47], off
	v_lshl_add_u64 v[46:47], v[46:47], 0, v[44:45]
	global_load_dwordx4 v[40:43], v[46:47], off
	global_load_dwordx4 v[4:7], v[4:5], off

; DI int otid() { int z; asm volatile("s_mov_b32 %0, 0" : "=s"(z)); return (int)threadIdx.x + z; }
; DI void cvt_tile(const CvtSeg& s, int tile, char* smem) {
;   float* T = (float*)smem;
;   const int tid = otid();
;   const int nkt = s.K >> 6;
;   const int kt = tile % nkt, nt = tile / nkt;
;   const int k0 = kt * 64, n0 = nt * 64;
;   __syncthreads();
; #pragma unroll
;   for (int i = 0; i < 4; ++i) {
;     const int k = i * 16 + (tid >> 4), n4 = (tid & 15) * 4;
;     float4 v = make_float4(0.f, 0.f, 0.f, 0.f);
;     if (n0 + n4 < s.ncols) {
;       v = *(const float4*)(s.src + (size_t)(k0 + k) * s.lds + s.sc0 + n0 + n4);
.LBB0_1101:
	s_load_dwordx2 s[12:13], s[60:61], 0x0
	s_mov_b32 s14, 0
	v_mov_b32_e32 v4, 0
	v_add_u32_e32 v10, s14, v189
	v_lshlrev_b32_e32 v0, 2, v10
	s_waitcnt lgkmcnt(0)
	s_add_u32 s15, s12, s90
	s_addc_u32 s13, s13, s11
	s_ashr_i32 s12, s37, 31
	s_lshr_b32 s12, s12, 27
	s_add_i32 s12, s37, s12
	s_and_b32 s14, s12, 0x3ffffe0
	s_lshl_b32 s16, s12, 1
	s_sub_i32 s12, s37, s14
	s_lshl_b32 s12, s12, 6
	s_and_b32 s14, s16, 0xffffffc0
	s_add_u32 s24, s15, s51
	s_addc_u32 s13, s13, 0
	s_ashr_i32 s15, s14, 31
	s_lshl_b64 s[16:17], s[14:15], 2
	v_and_b32_e32 v0, 60, v0
	s_add_u32 s16, s24, s16
	v_or_b32_e32 v2, s14, v0
	s_addc_u32 s17, s13, s17
	v_lshlrev_b32_e32 v0, 2, v0
	v_ashrrev_i32_e32 v11, 4, v10
	v_cmp_gt_i32_e32 vcc, s48, v2
	v_lshl_add_u64 v[8:9], s[16:17], 0, v[0:1]
	v_mov_b32_e32 v2, 0
	v_mov_b32_e32 v5, 0
	v_mov_b32_e32 v6, 0
	v_mov_b32_e32 v7, 0
	s_barrier
	s_and_saveexec_b64 s[16:17], vcc
	s_cbranch_execz .LBB0_1103
	v_add_u32_e32 v3, s12, v11
	v_mad_i64_i32 v[4:5], s[24:25], s38, v3, 0
	v_lshl_add_u64 v[4:5], v[4:5], 2, v[8:9]
	v_mov_b32_e32 v44, s38
	v_lshlrev_b32_e32 v44, 6, v44
	v_mov_b32_e32 v45, 0
	v_lshl_add_u64 v[46:47], v[4:5], 0, v[44:45]
	global_load_dwordx4 v[32:35], v[46:47], off
	v_lshl_add_u64 v[46:47], v[46:47], 0, v[44:45]
	global_load_dwordx4 v[36:39], v[46:47], off
	v_lshl_add_u64 v[46:47], v[46:47], 0, v[44:45]
	global_load_dwordx4 v[40:43], v[46:47], off
	global_load_dwordx4 v[4:7], v[4:5], off

; DI int otid() { int z; asm volatile("s_mov_b32 %0, 0" : "=s"(z)); return (int)threadIdx.x + z; }
; DI void cvt_tile(const CvtSeg& s, int tile, char* smem) {
;   float* T = (float*)smem;
;   const int tid = otid();
;   const int nkt = s.K >> 6;
;   const int kt = tile % nkt, nt = tile / nkt;
;   const int k0 = kt * 64, n0 = nt * 64;
;   __syncthreads();
; #pragma unroll
;   for (int i = 0; i < 4; ++i) {
;     const int k = i * 16 + (tid >> 4), n4 = (tid & 15) * 4;
;     float4 v = make_float4(0.f, 0.f, 0.f, 0.f);
;     if (n0 + n4 < s.ncols) {
;       v = *(const float4*)(s.src + (size_t)(k0 + k) * s.lds + s.sc0 + n0 + n4);
.LBB0_1114:
	s_load_dwordx2 s[12:13], s[60:61], 0x0
	s_mov_b32 s14, 0
	v_mov_b32_e32 v4, 0
	v_add_u32_e32 v10, s14, v189
	v_lshlrev_b32_e32 v0, 2, v10
	s_waitcnt lgkmcnt(0)
	s_add_u32 s15, s12, s90
	s_addc_u32 s13, s13, s11
	s_ashr_i32 s12, s36, 31
	s_lshr_b32 s12, s12, 27
	s_add_i32 s12, s36, s12
	s_and_b32 s14, s12, 0x3ffffe0
	s_lshl_b32 s16, s12, 1
	s_sub_i32 s12, s36, s14
	s_and_b32 s14, s16, 0xffffffc0
	v_and_b32_e32 v0, 60, v0
	v_or_b32_e32 v2, s14, v0
	v_readlane_b32 s16, v255, 0
	s_lshl_b32 s12, s12, 6
	v_lshlrev_b32_e32 v0, 2, v0
	v_cmp_gt_i32_e32 vcc, s16, v2
	v_readlane_b32 s16, v255, 20
	s_add_u32 s24, s15, s16
	s_addc_u32 s13, s13, 0
	s_ashr_i32 s15, s14, 31
	s_lshl_b64 s[16:17], s[14:15], 2
	s_add_u32 s16, s24, s16
	s_addc_u32 s17, s13, s17
	v_ashrrev_i32_e32 v11, 4, v10
	v_lshl_add_u64 v[8:9], s[16:17], 0, v[0:1]
	v_mov_b32_e32 v2, 0
	v_mov_b32_e32 v5, 0
	v_mov_b32_e32 v6, 0
	v_mov_b32_e32 v7, 0
	s_barrier
	s_and_saveexec_b64 s[16:17], vcc
	s_cbranch_execz .LBB0_1116
	v_add_u32_e32 v3, s12, v11
	v_mad_i64_i32 v[4:5], s[24:25], s38, v3, 0
	v_lshl_add_u64 v[4:5], v[4:5], 2, v[8:9]
	v_mov_b32_e32 v44, s38
	v_lshlrev_b32_e32 v44, 6, v44
	v_mov_b32_e32 v45, 0
	v_lshl_add_u64 v[46:47], v[4:5], 0, v[44:45]
	global_load_dwordx4 v[32:35], v[46:47], off
	v_lshl_add_u64 v[46:47], v[46:47], 0, v[44:45]
	global_load_dwordx4 v[36:39], v[46:47], off
	v_lshl_add_u64 v[46:47], v[46:47], 0, v[44:45]
	global_load_dwordx4 v[40:43], v[46:47], off
	global_load_dwordx4 v[4:7], v[4:5], off
